# gemm_out L1 epilogue: the tile's residual block is touched (16 dwordx4 per thread) at epilogue start so the 16 serialized per-site residual loads hit cache
# baseline (speedup 1.0000x reference)
; template <class Epi>
; DEV void gemm_tile(const bf16_t* __restrict__ A, int lda, const bf16_t* __restrict__ Bt, int ldb, int K, int m0, int n0,
;                    Epi& epi, char* smem) {
;     ...
; #pragma unroll
;   for (int i = 0; i < 4; i++)
; #pragma unroll
;     for (int j = 0; j < 4; j++) epi(m0 + wm * 64 + j * 16 + l15, n0 + wn * 64 + i * 16 + quad * 4, acc[i][j]);
;   DEV void operator()(int m, int n, f32x4 v) {
;     const float* src; int mr;
;     if (m < MM) { src = xin_main + (size_t)m * 1024 + n; mr = m >> 13; } else { src = xin_ctx + (size_t)(m - MM) * 1024 + n; mr = 2; }
;     float4 xo = *(const float4*)src;
;     float4 g = *(const float4*)(mod + (size_t)mr * 6144 + 2048 + n);
;     float4 r; r.x = xo.x + g.x * v[0]; r.y = xo.y + g.y * v[1]; r.z = xo.z + g.z * v[2]; r.w = xo.w + g.w * v[3];
;     *(float4*)(X + (size_t)m * 1024 + n) = r;
;   }
.LBB0_205:
	v_lshrrev_b32_e32 v184, 1, v141
	v_add_u32_e32 v184, s0, v184
	v_mov_b32_e32 v185, 0
	v_lshlrev_b64 v[184:185], 12, v[184:185]
	v_and_b32_e32 v186, 1, v141
	v_lshlrev_b32_e32 v186, 8, v186
	v_lshl_add_u32 v186, s13, 2, v186
	v_mov_b32_e32 v187, 0
	v_lshl_add_u64 v[184:185], v[184:185], 0, v[186:187]
	v_lshl_add_u64 v[184:185], s[28:29], 0, v[184:185]
	global_load_dwordx4 v[188:191], v[184:185], off
	global_load_dwordx4 v[188:191], v[184:185], off offset:16
	global_load_dwordx4 v[188:191], v[184:185], off offset:32
	global_load_dwordx4 v[188:191], v[184:185], off offset:48
	global_load_dwordx4 v[188:191], v[184:185], off offset:64
	global_load_dwordx4 v[188:191], v[184:185], off offset:80
	global_load_dwordx4 v[188:191], v[184:185], off offset:96
	global_load_dwordx4 v[188:191], v[184:185], off offset:112
	global_load_dwordx4 v[188:191], v[184:185], off offset:128
	global_load_dwordx4 v[188:191], v[184:185], off offset:144
	global_load_dwordx4 v[188:191], v[184:185], off offset:160
	global_load_dwordx4 v[188:191], v[184:185], off offset:176
	global_load_dwordx4 v[188:191], v[184:185], off offset:192
	global_load_dwordx4 v[188:191], v[184:185], off offset:208
	global_load_dwordx4 v[188:191], v[184:185], off offset:224
	global_load_dwordx4 v[188:191], v[184:185], off offset:240
	v_and_or_b32 v0, v141, 15, s0
	v_add_u32_e32 v44, v0, v142
	v_cmp_lt_i32_e64 s[38:39], s23, v44
	s_waitcnt vmcnt(7)
	v_add_u32_e32 v48, 0xffffc000, v44
	s_and_saveexec_b64 s[0:1], s[38:39]
	s_xor_b64 s[0:1], exec, s[0:1]
	v_mov_b32_e32 v49, v1
	v_lshlrev_b64 v[42:43], 12, v[48:49]
	v_mov_b32_e32 v45, v1
	v_lshl_add_u64 v[50:51], s[8:9], 0, v[42:43]
	v_lshlrev_b64 v[46:47], 12, v[44:45]
	s_or_saveexec_b64 s[0:1], s[0:1]
	v_ashrrev_i32_e32 v0, 13, v44
	v_mov_b64_e32 v[52:53], 0x3000
	v_ashrrev_i32_e32 v45, 31, v44
	v_mul_i32_i24_e32 v42, 0x1800, v0
	s_movk_i32 s19, 0x880
	s_xor_b64 exec, exec, s[0:1]
	v_lshlrev_b64 v[46:47], 12, v[44:45]
	v_ashrrev_i32_e32 v43, 31, v42
	v_lshl_add_u64 v[50:51], s[28:29], 0, v[46:47]
	v_mov_b64_e32 v[52:53], v[42:43]
	s_or_b64 exec, exec, s[0:1]
	v_lshrrev_b32_e32 v0, 2, v141
	v_and_b32_e32 v0, 12, v0
	v_or3_b32 v68, s13, v0, v140
	v_lshlrev_b32_e32 v0, 2, v68
	v_lshl_add_u64 v[52:53], v[52:53], 2, s[6:7]
	s_waitcnt vmcnt(6)
	v_lshl_add_u64 v[54:55], v[52:53], 0, v[0:1]
	v_add_co_u32_e32 v54, vcc, s21, v54
	v_lshl_add_u64 v[50:51], v[50:51], 0, v[0:1]
	s_nop 0
	v_addc_co_u32_e32 v55, vcc, 0, v55, vcc
	global_load_dwordx4 v[50:53], v[50:51], off
	v_lshl_add_u64 v[46:47], s[28:29], 0, v[46:47]
	global_load_dwordx4 v[54:57], v[54:55], off
	v_lshl_add_u64 v[46:47], v[46:47], 0, v[0:1]
	s_waitcnt vmcnt(0)
	v_pk_fma_f32 v[50:51], v[126:127], v[54:55], v[50:51]
	v_pk_fma_f32 v[52:53], v[128:129], v[56:57], v[52:53]
	global_store_dwordx4 v[46:47], v[50:53], off
	v_or_b32_e32 v46, 16, v44
	v_cmp_lt_i32_e64 s[40:41], s23, v46
	v_add_u32_e32 v52, 0xffffc010, v44
	s_and_saveexec_b64 s[0:1], s[40:41]
	s_xor_b64 s[0:1], exec, s[0:1]
	v_mov_b32_e32 v53, v1
	v_lshlrev_b64 v[50:51], 12, v[52:53]
	v_mov_b32_e32 v47, v1
	v_lshl_add_u64 v[54:55], s[8:9], 0, v[50:51]
	v_lshlrev_b64 v[50:51], 12, v[46:47]
	s_or_saveexec_b64 s[0:1], s[0:1]
	v_mov_b64_e32 v[56:57], 0x3000
	v_ashrrev_i32_e32 v47, 31, v46
	s_xor_b64 exec, exec, s[0:1]
	v_lshlrev_b64 v[50:51], 12, v[46:47]
	v_ashrrev_i32_e32 v43, 31, v42
	v_lshl_add_u64 v[54:55], s[28:29], 0, v[50:51]
	v_mov_b64_e32 v[56:57], v[42:43]
	s_or_b64 exec, exec, s[0:1]
	v_lshl_add_u64 v[56:57], v[56:57], 2, s[6:7]
	v_lshl_add_u64 v[58:59], v[56:57], 0, v[0:1]
	v_add_co_u32_e32 v58, vcc, s21, v58
	v_lshl_add_u64 v[54:55], v[54:55], 0, v[0:1]
	s_nop 0
	v_addc_co_u32_e32 v59, vcc, 0, v59, vcc
	global_load_dwordx4 v[54:57], v[54:55], off
	v_lshl_add_u64 v[50:51], s[28:29], 0, v[50:51]
	global_load_dwordx4 v[58:61], v[58:59], off
	v_lshl_add_u64 v[50:51], v[50:51], 0, v[0:1]
	s_waitcnt vmcnt(0)
	v_pk_fma_f32 v[54:55], v[122:123], v[58:59], v[54:55]
	v_pk_fma_f32 v[56:57], v[124:125], v[60:61], v[56:57]
	global_store_dwordx4 v[50:51], v[54:57], off
	v_or_b32_e32 v50, 32, v44
	v_cmp_lt_i32_e64 s[42:43], s23, v50
	v_add_u32_e32 v56, 0xffffc020, v44
	s_and_saveexec_b64 s[0:1], s[42:43]
	s_xor_b64 s[0:1], exec, s[0:1]
	v_mov_b32_e32 v57, v1
	v_lshlrev_b64 v[54:55], 12, v[56:57]
	v_mov_b32_e32 v51, v1
	v_lshl_add_u64 v[58:59], s[8:9], 0, v[54:55]
	v_lshlrev_b64 v[54:55], 12, v[50:51]
	s_or_saveexec_b64 s[0:1], s[0:1]
	v_mov_b64_e32 v[60:61], 0x3000
	v_ashrrev_i32_e32 v51, 31, v50
	s_xor_b64 exec, exec, s[0:1]
	v_lshlrev_b64 v[54:55], 12, v[50:51]
	v_ashrrev_i32_e32 v43, 31, v42
	v_lshl_add_u64 v[58:59], s[28:29], 0, v[54:55]
	v_mov_b64_e32 v[60:61], v[42:43]
	s_or_b64 exec, exec, s[0:1]
	v_lshl_add_u64 v[60:61], v[60:61], 2, s[6:7]
	v_lshl_add_u64 v[62:63], v[60:61], 0, v[0:1]
	v_add_co_u32_e32 v62, vcc, s21, v62
	v_lshl_add_u64 v[58:59], v[58:59], 0, v[0:1]
	s_nop 0
	v_addc_co_u32_e32 v63, vcc, 0, v63, vcc
	global_load_dwordx4 v[58:61], v[58:59], off
	v_lshl_add_u64 v[54:55], s[28:29], 0, v[54:55]
	global_load_dwordx4 v[62:65], v[62:63], off
	v_lshl_add_u64 v[54:55], v[54:55], 0, v[0:1]
	s_waitcnt vmcnt(0)
;   DEV void operator()(int m, int n, f32x4 v) {
;     const float* src; int mr;
;     if (m < MM) { src = xin_main + (size_t)m * 1024 + n; mr = m >> 13; } else { src = xin_ctx + (size_t)(m - MM) * 1024 + n; mr = 2; }
;     float4 xo = *(const float4*)src;
;     float4 g = *(const float4*)(mod + (size_t)mr * 6144 + 2048 + n);
;     float4 r; r.x = xo.x + g.x * v[0]; r.y = xo.y + g.y * v[1]; r.z = xo.z + g.z * v[2]; r.w = xo.w + g.w * v[3];
;     *(float4*)(X + (size_t)m * 1024 + n) = r;
;   }
	v_pk_fma_f32 v[58:59], v[118:119], v[62:63], v[58:59]
	v_pk_fma_f32 v[60:61], v[120:121], v[64:65], v[60:61]
	global_store_dwordx4 v[54:55], v[58:61], off
	v_or_b32_e32 v54, 48, v44
	v_cmp_lt_i32_e64 s[44:45], s23, v54
	v_add_u32_e32 v58, 0xffffc030, v44
	s_and_saveexec_b64 s[0:1], s[44:45]
	s_xor_b64 s[0:1], exec, s[0:1]
	v_mov_b32_e32 v59, v1
	v_lshlrev_b64 v[60:61], 12, v[58:59]
	v_mov_b32_e32 v55, v1
	v_lshl_add_u64 v[62:63], s[8:9], 0, v[60:61]
	v_lshlrev_b64 v[60:61], 12, v[54:55]
	s_or_saveexec_b64 s[0:1], s[0:1]
	v_mov_b64_e32 v[64:65], 0x3000
	v_ashrrev_i32_e32 v55, 31, v54
	s_xor_b64 exec, exec, s[0:1]
	v_lshlrev_b64 v[60:61], 12, v[54:55]
	v_ashrrev_i32_e32 v43, 31, v42
	v_lshl_add_u64 v[62:63], s[28:29], 0, v[60:61]
	v_mov_b64_e32 v[64:65], v[42:43]
	s_or_b64 exec, exec, s[0:1]
	v_lshl_add_u64 v[64:65], v[64:65], 2, s[6:7]
	v_lshl_add_u64 v[66:67], v[64:65], 0, v[0:1]
	v_add_co_u32_e32 v66, vcc, s21, v66
	v_lshl_add_u64 v[62:63], v[62:63], 0, v[0:1]
	s_nop 0
	v_addc_co_u32_e32 v67, vcc, 0, v67, vcc
	global_load_dwordx4 v[62:65], v[62:63], off
	v_lshl_add_u64 v[60:61], s[28:29], 0, v[60:61]
	global_load_dwordx4 v[70:73], v[66:67], off
	v_lshl_add_u64 v[66:67], v[60:61], 0, v[0:1]
	s_waitcnt vmcnt(0)
	v_pk_fma_f32 v[60:61], v[114:115], v[70:71], v[62:63]
	v_pk_fma_f32 v[62:63], v[116:117], v[72:73], v[64:65]
	global_store_dwordx4 v[66:67], v[60:63], off
	s_and_saveexec_b64 s[0:1], s[38:39]
	s_xor_b64 s[0:1], exec, s[0:1]
	v_mov_b32_e32 v49, v1
	v_lshlrev_b64 v[60:61], 12, v[48:49]
	v_mov_b32_e32 v62, v44
	v_mov_b32_e32 v63, v1
	v_lshl_add_u64 v[60:61], s[8:9], 0, v[60:61]
	v_lshlrev_b64 v[62:63], 12, v[62:63]
	s_or_saveexec_b64 s[0:1], s[0:1]
	v_mov_b64_e32 v[64:65], 0x3000
	s_xor_b64 exec, exec, s[0:1]
	v_lshlrev_b64 v[62:63], 12, v[44:45]
	v_ashrrev_i32_e32 v43, 31, v42
	v_lshl_add_u64 v[60:61], s[28:29], 0, v[62:63]
	v_mov_b64_e32 v[64:65], v[42:43]
	s_or_b64 exec, exec, s[0:1]
	v_or_b32_e32 v43, 16, v68
	v_lshl_add_u64 v[66:67], v[60:61], 0, v[0:1]
	v_lshl_add_u64 v[64:65], v[64:65], 2, s[6:7]
	v_lshlrev_b32_e32 v60, 2, v43
	v_mov_b32_e32 v61, v1
	v_lshl_add_u64 v[70:71], v[64:65], 0, v[60:61]
	v_add_co_u32_e32 v70, vcc, s21, v70
	global_load_dwordx4 v[64:67], v[66:67], off offset:64
	s_nop 0
	v_addc_co_u32_e32 v71, vcc, 0, v71, vcc
	global_load_dwordx4 v[70:73], v[70:71], off
	v_lshl_add_u64 v[62:63], s[28:29], 0, v[62:63]
	v_lshl_add_u64 v[78:79], v[62:63], 0, v[0:1]
	s_waitcnt vmcnt(0)
	v_pk_fma_f32 v[62:63], v[110:111], v[70:71], v[64:65]
	v_pk_fma_f32 v[64:65], v[112:113], v[72:73], v[66:67]
	global_store_dwordx4 v[78:79], v[62:65], off offset:64
	s_and_saveexec_b64 s[0:1], s[40:41]
	s_xor_b64 s[0:1], exec, s[0:1]
	v_mov_b32_e32 v53, v1
	v_lshlrev_b64 v[62:63], 12, v[52:53]
	v_lshl_add_u64 v[64:65], s[8:9], 0, v[62:63]
	v_mov_b32_e32 v62, v46
	v_mov_b32_e32 v63, v1
	v_lshlrev_b64 v[62:63], 12, v[62:63]
	s_or_saveexec_b64 s[0:1], s[0:1]
	v_mov_b64_e32 v[66:67], 0x3000
	s_xor_b64 exec, exec, s[0:1]
	v_lshlrev_b64 v[62:63], 12, v[46:47]
	v_ashrrev_i32_e32 v43, 31, v42
	v_lshl_add_u64 v[64:65], s[28:29], 0, v[62:63]
	v_mov_b64_e32 v[66:67], v[42:43]
	s_or_b64 exec, exec, s[0:1]
	v_lshl_add_u64 v[66:67], v[66:67], 2, s[6:7]
	v_mov_b32_e32 v61, v1
	v_lshl_add_u64 v[70:71], v[66:67], 0, v[60:61]
	v_add_co_u32_e32 v70, vcc, s21, v70
	v_lshl_add_u64 v[64:65], v[64:65], 0, v[0:1]
	s_nop 0
	v_addc_co_u32_e32 v71, vcc, 0, v71, vcc
	global_load_dwordx4 v[64:67], v[64:65], off offset:64
	v_lshl_add_u64 v[62:63], s[28:29], 0, v[62:63]
	global_load_dwordx4 v[70:73], v[70:71], off
	v_lshl_add_u64 v[78:79], v[62:63], 0, v[0:1]
	s_waitcnt vmcnt(0)
	v_pk_fma_f32 v[62:63], v[74:75], v[70:71], v[64:65]
	v_pk_fma_f32 v[64:65], v[76:77], v[72:73], v[66:67]
	global_store_dwordx4 v[78:79], v[62:65], off offset:64
	s_and_saveexec_b64 s[0:1], s[42:43]
	s_xor_b64 s[0:1], exec, s[0:1]
	v_mov_b32_e32 v57, v1
	v_lshlrev_b64 v[62:63], 12, v[56:57]
	v_lshl_add_u64 v[64:65], s[8:9], 0, v[62:63]
	v_mov_b32_e32 v62, v50
	v_mov_b32_e32 v63, v1
	v_lshlrev_b64 v[62:63], 12, v[62:63]
	s_or_saveexec_b64 s[0:1], s[0:1]
	v_mov_b64_e32 v[66:67], 0x3000
	s_xor_b64 exec, exec, s[0:1]
	v_lshlrev_b64 v[62:63], 12, v[50:51]
	v_ashrrev_i32_e32 v43, 31, v42
	v_lshl_add_u64 v[64:65], s[28:29], 0, v[62:63]
	v_mov_b64_e32 v[66:67], v[42:43]
	s_or_b64 exec, exec, s[0:1]
	v_lshl_add_u64 v[66:67], v[66:67], 2, s[6:7]
	v_mov_b32_e32 v61, v1
	v_lshl_add_u64 v[70:71], v[66:67], 0, v[60:61]
	v_add_co_u32_e32 v70, vcc, s21, v70
	v_lshl_add_u64 v[64:65], v[64:65], 0, v[0:1]
	s_nop 0
	v_addc_co_u32_e32 v71, vcc, 0, v71, vcc
	global_load_dwordx4 v[64:67], v[64:65], off offset:64
	v_lshl_add_u64 v[62:63], s[28:29], 0, v[62:63]
	global_load_dwordx4 v[70:73], v[70:71], off
	v_lshl_add_u64 v[62:63], v[62:63], 0, v[0:1]
	s_waitcnt vmcnt(0)
	v_pk_fma_f32 v[38:39], v[38:39], v[70:71], v[64:65]
	v_pk_fma_f32 v[40:41], v[40:41], v[72:73], v[66:67]
	global_store_dwordx4 v[62:63], v[38:41], off offset:64
	s_and_saveexec_b64 s[0:1], s[44:45]
	s_xor_b64 s[0:1], exec, s[0:1]
	v_mov_b32_e32 v59, v1
	v_lshlrev_b64 v[38:39], 12, v[58:59]
	v_lshl_add_u64 v[40:41], s[8:9], 0, v[38:39]
	v_mov_b32_e32 v38, v54
	v_mov_b32_e32 v39, v1
	v_lshlrev_b64 v[38:39], 12, v[38:39]
	s_or_saveexec_b64 s[0:1], s[0:1]
	v_mov_b64_e32 v[62:63], 0x3000
	s_xor_b64 exec, exec, s[0:1]
	v_lshlrev_b64 v[38:39], 12, v[54:55]
	v_ashrrev_i32_e32 v43, 31, v42
	v_lshl_add_u64 v[40:41], s[28:29], 0, v[38:39]
	v_mov_b64_e32 v[62:63], v[42:43]
	s_or_b64 exec, exec, s[0:1]
	v_lshl_add_u64 v[62:63], v[62:63], 2, s[6:7]
	v_mov_b32_e32 v61, v1
	v_lshl_add_u64 v[40:41], v[40:41], 0, v[0:1]
	v_lshl_add_u64 v[64:65], v[62:63], 0, v[60:61]
	global_load_dwordx4 v[60:63], v[40:41], off offset:64
	v_add_co_u32_e32 v40, vcc, s21, v64
	v_lshl_add_u64 v[38:39], s[28:29], 0, v[38:39]
	s_nop 0
	v_addc_co_u32_e32 v41, vcc, 0, v65, vcc
	global_load_dwordx4 v[64:67], v[40:41], off
	v_lshl_add_u64 v[38:39], v[38:39], 0, v[0:1]
	s_waitcnt vmcnt(0)
;   DEV void operator()(int m, int n, f32x4 v) {
;     const float* src; int mr;
;     if (m < MM) { src = xin_main + (size_t)m * 1024 + n; mr = m >> 13; } else { src = xin_ctx + (size_t)(m - MM) * 1024 + n; mr = 2; }
;     float4 xo = *(const float4*)src;
;     float4 g = *(const float4*)(mod + (size_t)mr * 6144 + 2048 + n);
;     float4 r; r.x = xo.x + g.x * v[0]; r.y = xo.y + g.y * v[1]; r.z = xo.z + g.z * v[2]; r.w = xo.w + g.w * v[3];
;     *(float4*)(X + (size_t)m * 1024 + n) = r;
;   }
	v_pk_fma_f32 v[34:35], v[34:35], v[64:65], v[60:61]
	v_pk_fma_f32 v[36:37], v[36:37], v[66:67], v[62:63]
	global_store_dwordx4 v[38:39], v[34:37], off offset:64
	s_and_saveexec_b64 s[0:1], s[38:39]
	s_xor_b64 s[0:1], exec, s[0:1]
	v_mov_b32_e32 v49, v1
	v_lshlrev_b64 v[34:35], 12, v[48:49]
	v_mov_b32_e32 v36, v44
	v_mov_b32_e32 v37, v1
	v_lshl_add_u64 v[34:35], s[8:9], 0, v[34:35]
	v_lshlrev_b64 v[36:37], 12, v[36:37]
	s_or_saveexec_b64 s[0:1], s[0:1]
	v_mov_b64_e32 v[38:39], 0x3000
	s_xor_b64 exec, exec, s[0:1]
	v_lshlrev_b64 v[36:37], 12, v[44:45]
	v_ashrrev_i32_e32 v43, 31, v42
	v_lshl_add_u64 v[34:35], s[28:29], 0, v[36:37]
	v_mov_b64_e32 v[38:39], v[42:43]
	s_or_b64 exec, exec, s[0:1]
	v_or_b32_e32 v43, 32, v68
	v_lshl_add_u64 v[40:41], v[34:35], 0, v[0:1]
	v_lshl_add_u64 v[38:39], v[38:39], 2, s[6:7]
	v_lshlrev_b32_e32 v34, 2, v43
	v_mov_b32_e32 v35, v1
	v_lshl_add_u64 v[60:61], v[38:39], 0, v[34:35]
	v_add_co_u32_e32 v60, vcc, s21, v60
	global_load_dwordx4 v[38:41], v[40:41], off offset:128
	s_nop 0
	v_addc_co_u32_e32 v61, vcc, 0, v61, vcc
	global_load_dwordx4 v[60:63], v[60:61], off
	v_lshl_add_u64 v[36:37], s[28:29], 0, v[36:37]
	v_lshl_add_u64 v[36:37], v[36:37], 0, v[0:1]
	s_waitcnt vmcnt(0)
	v_pk_fma_f32 v[30:31], v[30:31], v[60:61], v[38:39]
	v_pk_fma_f32 v[32:33], v[32:33], v[62:63], v[40:41]
	global_store_dwordx4 v[36:37], v[30:33], off offset:128
	s_and_saveexec_b64 s[0:1], s[40:41]
	s_xor_b64 s[0:1], exec, s[0:1]
	v_mov_b32_e32 v53, v1
	v_lshlrev_b64 v[30:31], 12, v[52:53]
	v_lshl_add_u64 v[32:33], s[8:9], 0, v[30:31]
	v_mov_b32_e32 v30, v46
	v_mov_b32_e32 v31, v1
	v_lshlrev_b64 v[30:31], 12, v[30:31]
	s_or_saveexec_b64 s[0:1], s[0:1]
	v_mov_b64_e32 v[36:37], 0x3000
	s_xor_b64 exec, exec, s[0:1]
	v_lshlrev_b64 v[30:31], 12, v[46:47]
	v_ashrrev_i32_e32 v43, 31, v42
	v_lshl_add_u64 v[32:33], s[28:29], 0, v[30:31]
	v_mov_b64_e32 v[36:37], v[42:43]
	s_or_b64 exec, exec, s[0:1]
	v_lshl_add_u64 v[36:37], v[36:37], 2, s[6:7]
	v_mov_b32_e32 v35, v1
	v_lshl_add_u64 v[32:33], v[32:33], 0, v[0:1]
	v_lshl_add_u64 v[40:41], v[36:37], 0, v[34:35]
	global_load_dwordx4 v[36:39], v[32:33], off offset:128
	v_add_co_u32_e32 v32, vcc, s21, v40
	v_lshl_add_u64 v[30:31], s[28:29], 0, v[30:31]
	s_nop 0
	v_addc_co_u32_e32 v33, vcc, 0, v41, vcc
	global_load_dwordx4 v[60:63], v[32:33], off
	v_lshl_add_u64 v[30:31], v[30:31], 0, v[0:1]
	s_waitcnt vmcnt(0)
	v_pk_fma_f32 v[26:27], v[26:27], v[60:61], v[36:37]
	v_pk_fma_f32 v[28:29], v[28:29], v[62:63], v[38:39]
	global_store_dwordx4 v[30:31], v[26:29], off offset:128
	s_and_saveexec_b64 s[0:1], s[42:43]
	s_xor_b64 s[0:1], exec, s[0:1]
	v_mov_b32_e32 v57, v1
	v_lshlrev_b64 v[26:27], 12, v[56:57]
	v_lshl_add_u64 v[28:29], s[8:9], 0, v[26:27]
	v_mov_b32_e32 v26, v50
	v_mov_b32_e32 v27, v1
	v_lshlrev_b64 v[26:27], 12, v[26:27]
	s_or_saveexec_b64 s[0:1], s[0:1]
	v_mov_b64_e32 v[30:31], 0x3000
	s_xor_b64 exec, exec, s[0:1]
	v_lshlrev_b64 v[26:27], 12, v[50:51]
	v_ashrrev_i32_e32 v43, 31, v42
	v_lshl_add_u64 v[28:29], s[28:29], 0, v[26:27]
	v_mov_b64_e32 v[30:31], v[42:43]
	s_or_b64 exec, exec, s[0:1]
	v_lshl_add_u64 v[30:31], v[30:31], 2, s[6:7]
	v_mov_b32_e32 v35, v1
	v_lshl_add_u64 v[32:33], v[30:31], 0, v[34:35]
	v_add_co_u32_e32 v32, vcc, s21, v32
	v_lshl_add_u64 v[28:29], v[28:29], 0, v[0:1]
	s_nop 0
	v_addc_co_u32_e32 v33, vcc, 0, v33, vcc
	global_load_dwordx4 v[28:31], v[28:29], off offset:128
	v_lshl_add_u64 v[26:27], s[28:29], 0, v[26:27]
	global_load_dwordx4 v[36:39], v[32:33], off
	v_lshl_add_u64 v[26:27], v[26:27], 0, v[0:1]
	s_waitcnt vmcnt(0)
	v_pk_fma_f32 v[22:23], v[22:23], v[36:37], v[28:29]
	v_pk_fma_f32 v[24:25], v[24:25], v[38:39], v[30:31]
	global_store_dwordx4 v[26:27], v[22:25], off offset:128
	s_and_saveexec_b64 s[0:1], s[44:45]
	s_xor_b64 s[0:1], exec, s[0:1]
	v_mov_b32_e32 v59, v1
	v_lshlrev_b64 v[22:23], 12, v[58:59]
	v_lshl_add_u64 v[24:25], s[8:9], 0, v[22:23]
	v_mov_b32_e32 v22, v54
	v_mov_b32_e32 v23, v1
	v_lshlrev_b64 v[22:23], 12, v[22:23]
	s_or_saveexec_b64 s[0:1], s[0:1]
	v_mov_b64_e32 v[26:27], 0x3000
	s_xor_b64 exec, exec, s[0:1]
	v_lshlrev_b64 v[22:23], 12, v[54:55]
	v_ashrrev_i32_e32 v43, 31, v42
	v_lshl_add_u64 v[24:25], s[28:29], 0, v[22:23]
	v_mov_b64_e32 v[26:27], v[42:43]
	s_or_b64 exec, exec, s[0:1]
	v_lshl_add_u64 v[26:27], v[26:27], 2, s[6:7]
	v_mov_b32_e32 v35, v1
	v_lshl_add_u64 v[28:29], v[26:27], 0, v[34:35]
	v_add_co_u32_e32 v28, vcc, s21, v28
	v_lshl_add_u64 v[24:25], v[24:25], 0, v[0:1]
	s_nop 0
	v_addc_co_u32_e32 v29, vcc, 0, v29, vcc
	global_load_dwordx4 v[24:27], v[24:25], off offset:128
	v_lshl_add_u64 v[22:23], s[28:29], 0, v[22:23]
	global_load_dwordx4 v[28:31], v[28:29], off
	v_lshl_add_u64 v[22:23], v[22:23], 0, v[0:1]
	s_waitcnt vmcnt(0)
;   DEV void operator()(int m, int n, f32x4 v) {
;     const float* src; int mr;
;     if (m < MM) { src = xin_main + (size_t)m * 1024 + n; mr = m >> 13; } else { src = xin_ctx + (size_t)(m - MM) * 1024 + n; mr = 2; }
;     float4 xo = *(const float4*)src;
;     float4 g = *(const float4*)(mod + (size_t)mr * 6144 + 2048 + n);
;     float4 r; r.x = xo.x + g.x * v[0]; r.y = xo.y + g.y * v[1]; r.z = xo.z + g.z * v[2]; r.w = xo.w + g.w * v[3];
;     *(float4*)(X + (size_t)m * 1024 + n) = r;
;   }
	v_pk_fma_f32 v[18:19], v[18:19], v[28:29], v[24:25]
	v_pk_fma_f32 v[20:21], v[20:21], v[30:31], v[26:27]
	global_store_dwordx4 v[22:23], v[18:21], off offset:128
	s_and_saveexec_b64 s[0:1], s[38:39]
	s_xor_b64 s[0:1], exec, s[0:1]
	v_mov_b32_e32 v49, v1
	v_lshlrev_b64 v[18:19], 12, v[48:49]
	v_mov_b32_e32 v45, v1
	v_lshl_add_u64 v[18:19], s[8:9], 0, v[18:19]
	v_lshlrev_b64 v[20:21], 12, v[44:45]
	s_or_saveexec_b64 s[0:1], s[0:1]
	v_mov_b64_e32 v[22:23], 0x3000
	s_xor_b64 exec, exec, s[0:1]
	v_lshlrev_b64 v[20:21], 12, v[44:45]
	v_ashrrev_i32_e32 v43, 31, v42
	v_lshl_add_u64 v[18:19], s[28:29], 0, v[20:21]
	v_mov_b64_e32 v[22:23], v[42:43]
	s_or_b64 exec, exec, s[0:1]
	v_or_b32_e32 v26, 48, v68
	v_lshl_add_u64 v[24:25], v[18:19], 0, v[0:1]
	v_lshl_add_u64 v[22:23], v[22:23], 2, s[6:7]
	v_lshlrev_b32_e32 v18, 2, v26
	v_mov_b32_e32 v19, v1
	v_lshl_add_u64 v[26:27], v[22:23], 0, v[18:19]
	v_add_co_u32_e32 v26, vcc, s21, v26
	global_load_dwordx4 v[22:25], v[24:25], off offset:192
	s_nop 0
	v_addc_co_u32_e32 v27, vcc, 0, v27, vcc
	global_load_dwordx4 v[26:29], v[26:27], off
	v_lshl_add_u64 v[20:21], s[28:29], 0, v[20:21]
	v_lshl_add_u64 v[20:21], v[20:21], 0, v[0:1]
	s_waitcnt vmcnt(0)
	v_pk_fma_f32 v[14:15], v[14:15], v[26:27], v[22:23]
	v_pk_fma_f32 v[16:17], v[16:17], v[28:29], v[24:25]
	global_store_dwordx4 v[20:21], v[14:17], off offset:192
	s_and_saveexec_b64 s[0:1], s[40:41]
	s_xor_b64 s[0:1], exec, s[0:1]
	v_mov_b32_e32 v53, v1
	v_lshlrev_b64 v[14:15], 12, v[52:53]
	v_mov_b32_e32 v47, v1
	v_lshl_add_u64 v[16:17], s[8:9], 0, v[14:15]
	v_lshlrev_b64 v[14:15], 12, v[46:47]
	s_or_saveexec_b64 s[0:1], s[0:1]
	v_mov_b64_e32 v[20:21], 0x3000
	s_xor_b64 exec, exec, s[0:1]
	v_lshlrev_b64 v[14:15], 12, v[46:47]
	v_ashrrev_i32_e32 v43, 31, v42
	v_lshl_add_u64 v[16:17], s[28:29], 0, v[14:15]
	v_mov_b64_e32 v[20:21], v[42:43]
	s_or_b64 exec, exec, s[0:1]
	v_lshl_add_u64 v[20:21], v[20:21], 2, s[6:7]
	v_mov_b32_e32 v19, v1
	v_lshl_add_u64 v[16:17], v[16:17], 0, v[0:1]
	v_lshl_add_u64 v[24:25], v[20:21], 0, v[18:19]
	global_load_dwordx4 v[20:23], v[16:17], off offset:192
	v_add_co_u32_e32 v16, vcc, s21, v24
	v_lshl_add_u64 v[14:15], s[28:29], 0, v[14:15]
	s_nop 0
	v_addc_co_u32_e32 v17, vcc, 0, v25, vcc
	global_load_dwordx4 v[24:27], v[16:17], off
	v_lshl_add_u64 v[14:15], v[14:15], 0, v[0:1]
	s_waitcnt vmcnt(0)
	v_pk_fma_f32 v[10:11], v[10:11], v[24:25], v[20:21]
	v_pk_fma_f32 v[12:13], v[12:13], v[26:27], v[22:23]
	global_store_dwordx4 v[14:15], v[10:13], off offset:192
	s_and_saveexec_b64 s[0:1], s[42:43]
	s_xor_b64 s[0:1], exec, s[0:1]
	v_mov_b32_e32 v57, v1
	v_lshlrev_b64 v[10:11], 12, v[56:57]
	v_mov_b32_e32 v51, v1
	v_lshl_add_u64 v[12:13], s[8:9], 0, v[10:11]
	v_lshlrev_b64 v[10:11], 12, v[50:51]
	s_or_saveexec_b64 s[0:1], s[0:1]
	v_mov_b64_e32 v[14:15], 0x3000
	s_xor_b64 exec, exec, s[0:1]
	v_lshlrev_b64 v[10:11], 12, v[50:51]
	v_ashrrev_i32_e32 v43, 31, v42
	v_lshl_add_u64 v[12:13], s[28:29], 0, v[10:11]
	v_mov_b64_e32 v[14:15], v[42:43]
	s_or_b64 exec, exec, s[0:1]
	v_lshl_add_u64 v[14:15], v[14:15], 2, s[6:7]
	v_mov_b32_e32 v19, v1
	v_lshl_add_u64 v[16:17], v[14:15], 0, v[18:19]
	v_add_co_u32_e32 v16, vcc, s21, v16
	v_lshl_add_u64 v[12:13], v[12:13], 0, v[0:1]
	s_nop 0
	v_addc_co_u32_e32 v17, vcc, 0, v17, vcc
	global_load_dwordx4 v[12:15], v[12:13], off offset:192
	v_lshl_add_u64 v[10:11], s[28:29], 0, v[10:11]
	global_load_dwordx4 v[20:23], v[16:17], off
	v_lshl_add_u64 v[10:11], v[10:11], 0, v[0:1]
	s_waitcnt vmcnt(0)
	v_pk_fma_f32 v[6:7], v[6:7], v[20:21], v[12:13]
	v_pk_fma_f32 v[8:9], v[8:9], v[22:23], v[14:15]
	global_store_dwordx4 v[10:11], v[6:9], off offset:192
	s_and_saveexec_b64 s[0:1], s[44:45]
	s_xor_b64 s[0:1], exec, s[0:1]
	v_mov_b32_e32 v59, v1
	v_lshlrev_b64 v[6:7], 12, v[58:59]
	v_mov_b32_e32 v55, v1
	v_lshl_add_u64 v[8:9], s[8:9], 0, v[6:7]
	v_lshlrev_b64 v[6:7], 12, v[54:55]
	s_or_saveexec_b64 s[0:1], s[0:1]
	v_mov_b64_e32 v[10:11], 0x3000
	s_xor_b64 exec, exec, s[0:1]
	s_cbranch_execz .LBB0_196
	v_lshlrev_b64 v[6:7], 12, v[54:55]
	v_ashrrev_i32_e32 v43, 31, v42
	v_lshl_add_u64 v[8:9], s[28:29], 0, v[6:7]
	v_mov_b64_e32 v[10:11], v[42:43]
	s_branch .LBB0_196
